# t17 + attention VALU diet: softmax scale multiply applied once after row-max (bit-identical), ring-wrap and buffer base folded into one SGPR so K/V LDS addresses take 1 VALU each (A and B loops)
# speedup vs baseline: 1.0043x; 1.0043x over previous
; #define LAS __attribute__((address_space(3)))
; #define MFMA32(a, b, c) __builtin_amdgcn_mfma_f32_32x32x16_bf16((a), (b), (c), 0, 0, 0)
; #define WG_BAR() do { asm volatile("s_waitcnt lgkmcnt(0)" ::: "memory"); __builtin_amdgcn_s_barrier(); asm volatile("" ::: "memory"); } while (0)
; template <class ScoreFn>
; __device__ __forceinline__ void attn_step(AttnState& st, const bf16x8 (&qf)[4], LAS unsigned char* kb, LAS unsigned char* vb, int lane, const ScoreFn& sf) {
;     ...
;     LAS unsigned char* kp = kb + r * KVP; const int kx = (h ^ (r & 7)) << 4;
; #pragma unroll
;     for (int ds = 0; ds < 4; ++ds) {
;         const bf16x8 k0 = *(const LAS bf16x8*)(kp + (kx ^ (ds << 5))), k1 = *(const LAS bf16x8*)(kp + 32 * KVP + (kx ^ (ds << 5)));
;         s0 = MFMA32(k0, qf[ds], s0); s1 = MFMA32(k1, qf[ds], s1);
;     }
;     float mt = NEG_BIG;
;     __builtin_amdgcn_sched_barrier(0);
; #pragma unroll
;     for (int i = 0; i < 16; ++i) { s0[i] = sf(s0[i], (i & 3) + 8 * (i >> 2), h, r); mt = fmaxf(mt, s0[i]); if ((i & 7) == 7) __builtin_amdgcn_sched_barrier(0); }
; #pragma unroll
;     for (int i = 0; i < 16; ++i) { s1[i] = sf(s1[i], 32 + (i & 3) + 8 * (i >> 2), h, r); mt = fmaxf(mt, s1[i]); if ((i & 7) == 7) __builtin_amdgcn_sched_barrier(0); }
;     mt = fmaxf(mt, __shfl_xor(mt, 32));
;     const float mn = fmaxf(st.m, mt), alpha = __builtin_amdgcn_exp2f(st.m - mn);
;     float ps = 0.f;
; #pragma unroll
;     for (int i = 0; i < 16; ++i) { s0[i] = __builtin_amdgcn_exp2f(s0[i] - mn); s1[i] = __builtin_amdgcn_exp2f(s1[i] - mn); ps += s0[i] + s1[i]; }
; template <bool ISB>
; __device__ __forceinline__ void attn_wg_item(Frame& F, int l, int idx) {
;     ...
;     AttnState st;
; #pragma unroll
;     for (int i = 0; i < 16; ++i) { st.o0[i] = 0.f; st.o1[i] = 0.f; }
;     st.m = NEG_BIG; st.l = 0.f;
; #pragma unroll
;     for (int t = 0; t < ATT_D; ++t) ATT_DMA(t);
;     if (ISB && lat) {
;         const float* bsrc = KIN(I_NBBIAS) + (size_t)(l * 8 + (ix & 7)) * 465;
;         if (tid < 465) tab[64 + tid] = bsrc[tid] * LOG2E; }
;     for (int s = 0; s < NS; ++s) {
;         ATT_DMA(s + ATT_D);
;         asm volatile("s_waitcnt vmcnt(8)" ::: "memory");
;         WG_BAR();
;         LAS unsigned char* cur = ring + (s % ATT_NB) * KV_BUF;
;         if (s >= nloc) { ScorePlain sf; attn_step(st, qf, cur, cur + KV_TILE, lane, sf); }
.LBB0_581:
	s_mul_hi_u32 s1, s16, 0xaaaaaaab
	s_mul_hi_u32 s2, s13, 0xaaaaaaab
	s_lshr_b32 s1, s1, 2
	s_lshr_b32 s2, s2, 2
	s_mul_i32 s1, s1, 0x18000
	s_mul_i32 s2, s2, 0x18000
	v_readlane_b32 s3, v253, 15
	s_sub_i32 s1, s15, s1
	v_add3_u32 v126, s1, v104, v89
	v_add3_u32 v125, s1, v96, v89
	v_add3_u32 v127, s1, v103, v89
	v_add3_u32 v124, s1, v95, v89
	v_add3_u32 v122, s1, v102, v89
	v_add3_u32 v123, s1, v101, v89
	v_add3_u32 v119, s1, v94, v89
	v_add3_u32 v120, s1, v93, v89
	v_add3_u32 v117, s1, v100, v89
	v_add3_u32 v118, s1, v99, v89
	v_add3_u32 v115, s1, v92, v89
	v_add3_u32 v116, s1, v91, v89
	v_add3_u32 v113, s1, v98, v89
	v_add3_u32 v114, s1, v97, v89
	v_add3_u32 v111, s1, v90, v89
	v_add3_u32 v112, s1, v88, v89
	v_add_u32_e32 v128, s1, v105
	s_sub_i32 s8, s3, s2
	v_add_u32_e32 v130, s1, v106
	v_add_u32_e32 v131, s1, v107
	v_add_u32_e32 v132, s1, v108
	s_add_i32 s1, s16, 4
	s_cmp_lt_i32 s16, s11
	s_cselect_b64 s[2:3], -1, 0
	s_and_b64 vcc, s[2:3], exec
	s_cselect_b32 s1, s1, s12
	s_cmp_lt_i32 s1, s11
	s_cselect_b32 s2, 0, s11
	s_cselect_b32 s3, s10, 0x2000
	s_sub_i32 s1, s1, s2
	s_lshl_b32 s1, s1, 6
	s_add_i32 s1, s1, s3
	s_add_i32 s2, s15, s8
	v_mov_b32_e32 v84, v2
	v_mov_b32_e32 v85, v3
	s_add_i32 s8, s2, 0
	v_mad_i64_i32 v[2:3], s[2:3], s1, v249, v[50:51]
	s_add_i32 m0, s8, 0x10000
	v_lshl_add_u64 v[4:5], v[2:3], 0, s[18:19]
	global_load_lds_dwordx4 v[4:5], off
	v_lshl_add_u64 v[2:3], v[2:3], 0, s[20:21]
	s_add_i32 m0, s8, 0x12000
	v_mov_b32_e32 v82, v18
	global_load_lds_dwordx4 v[2:3], off
	s_waitcnt vmcnt(8)
	s_waitcnt lgkmcnt(0)
	s_barrier
	v_mov_b32_e32 v83, v19
	s_mov_b64 s[8:9], -1
	s_cbranch_vccnz .LBB0_583
	s_mov_b32 s1, 0
	v_add_u32_e32 v6, s1, v132
	ds_read_b128 v[2:5], v6
	ds_read_b128 v[18:21], v6 offset:4096
	v_add_u32_e32 v26, s1, v131
	ds_read_b128 v[22:25], v26
	ds_read_b128 v[134:137], v26 offset:4096
	v_add_u32_e32 v27, s1, v130
	v_add_u32_e32 v26, s1, v128
	s_waitcnt lgkmcnt(0)
	v_mfma_f32_32x32x16_bf16 v[2:17], v[2:5], v[34:37], 0
	ds_read_b128 v[138:141], v27 offset:4096
	v_mfma_f32_32x32x16_bf16 v[2:17], v[22:25], v[38:41], v[2:17]
	ds_read_b128 v[22:25], v27
	s_waitcnt lgkmcnt(0)
	v_mfma_f32_32x32x16_bf16 v[2:17], v[22:25], v[42:45], v[2:17]
	ds_read_b128 v[22:25], v26
	ds_read_b128 v[142:145], v26 offset:4096
	s_waitcnt lgkmcnt(0)
	v_mfma_f32_32x32x16_bf16 v[2:17], v[22:25], v[46:49], v[2:17]
	v_mfma_f32_32x32x16_bf16 v[18:33], v[18:21], v[34:37], 0
	v_mfma_f32_32x32x16_bf16 v[18:33], v[134:137], v[38:41], v[18:33]
	v_mfma_f32_32x32x16_bf16 v[18:33], v[138:141], v[42:45], v[18:33]
	v_mfma_f32_32x32x16_bf16 v[18:33], v[142:145], v[46:49], v[18:33]
	s_nop 7
	s_mov_b32 s1, 0xf149f2ca
	v_max3_f32 v66, v2, v3, v4
	v_max3_f32 v66, v66, v5, v6
	v_max3_f32 v66, v66, v7, v8
	v_max3_f32 v66, v66, v9, v10
	v_max3_f32 v66, v66, v11, v12
	v_max3_f32 v66, v66, v13, v14
	v_max3_f32 v66, v66, v15, v16
	v_max3_f32 v66, v66, v17, v18
	v_max3_f32 v66, v66, v19, v20
	v_max3_f32 v66, v66, v21, v22
	v_max3_f32 v66, v66, v23, v24
	v_max3_f32 v66, v66, v25, v26
	v_max3_f32 v66, v66, v27, v28
	v_max3_f32 v66, v66, v29, v30
	v_max3_f32 v66, v66, v31, v32
	v_max_f32_e32 v66, v66, v33
	v_cmp_lt_i32_e32 vcc, v242, v241
	v_mul_f32_e32 v66, 0x3e38aa3b, v66
	v_max_f32_e32 v66, s1, v66
	v_cndmask_b32_e32 v121, v240, v242, vcc
	v_lshlrev_b32_e32 v121, 2, v121
	ds_bpermute_b32 v121, v121, v66
	s_waitcnt lgkmcnt(0)
	v_max3_f32 v121, v110, v66, v121
	v_fma_f32 v2, v2, s0, -v121
	v_exp_f32_e32 v133, v2
	v_fma_f32 v2, v18, s0, -v121
	v_exp_f32_e32 v165, v2
	v_fma_f32 v2, v3, s0, -v121
	v_exp_f32_e32 v66, v2
	v_fma_f32 v2, v19, s0, -v121
	v_exp_f32_e32 v142, v2
	v_add_f32_e32 v143, v165, v133
	v_pk_add_f32 v[2:3], v[142:143], v[66:67]
	s_nop 0
	v_pk_add_f32 v[136:137], v[2:3], v[2:3] op_sel_hi:[0,1]
	v_fma_f32 v2, v4, s0, -v121
	v_exp_f32_e32 v135, v2
	v_fma_f32 v2, v20, s0, -v121
	v_exp_f32_e32 v143, v2
	v_fma_f32 v2, v5, s0, -v121
	v_exp_f32_e32 v136, v2
	v_fma_f32 v2, v21, s0, -v121
	v_exp_f32_e32 v144, v2
	v_add_f32_e32 v145, v143, v135
	v_pk_add_f32 v[2:3], v[144:145], v[136:137]
	s_nop 0
	v_pk_add_f32 v[138:139], v[2:3], v[2:3] op_sel_hi:[0,1]
	v_fma_f32 v2, v6, s0, -v121
	v_exp_f32_e32 v137, v2
	v_fma_f32 v2, v22, s0, -v121
	v_exp_f32_e32 v145, v2
	v_fma_f32 v2, v7, s0, -v121
	v_exp_f32_e32 v138, v2
	v_fma_f32 v2, v23, s0, -v121
	v_exp_f32_e32 v146, v2
	v_add_f32_e32 v147, v145, v137
	v_pk_add_f32 v[2:3], v[146:147], v[138:139]
	s_nop 0
	v_pk_add_f32 v[140:141], v[2:3], v[2:3] op_sel_hi:[0,1]
	v_fma_f32 v2, v8, s0, -v121
	v_exp_f32_e32 v139, v2
	v_fma_f32 v2, v24, s0, -v121
	v_exp_f32_e32 v147, v2
	v_fma_f32 v2, v9, s0, -v121
	v_exp_f32_e32 v140, v2
	v_fma_f32 v2, v25, s0, -v121
	v_exp_f32_e32 v148, v2
	v_add_f32_e32 v149, v147, v139
	v_pk_add_f32 v[2:3], v[148:149], v[140:141]
	s_nop 0
	v_pk_add_f32 v[150:151], v[2:3], v[2:3] op_sel_hi:[0,1]
	v_fma_f32 v2, v10, s0, -v121
	v_exp_f32_e32 v141, v2
	v_fma_f32 v2, v26, s0, -v121
	v_exp_f32_e32 v149, v2
	v_fma_f32 v2, v11, s0, -v121
	v_exp_f32_e32 v150, v2
	v_fma_f32 v2, v27, s0, -v121
	v_exp_f32_e32 v152, v2
	v_add_f32_e32 v153, v149, v141
	v_pk_add_f32 v[2:3], v[152:153], v[150:151]
	s_nop 0
	v_pk_add_f32 v[154:155], v[2:3], v[2:3] op_sel_hi:[0,1]
	v_fma_f32 v2, v12, s0, -v121
	v_exp_f32_e32 v151, v2
	v_fma_f32 v2, v28, s0, -v121
	v_exp_f32_e32 v153, v2
	v_fma_f32 v2, v13, s0, -v121
	v_exp_f32_e32 v154, v2
	v_fma_f32 v2, v29, s0, -v121
	v_exp_f32_e32 v156, v2
	v_add_f32_e32 v157, v153, v151
	v_pk_add_f32 v[2:3], v[156:157], v[154:155]
	s_nop 0
	v_pk_add_f32 v[158:159], v[2:3], v[2:3] op_sel_hi:[0,1]
	v_fma_f32 v2, v14, s0, -v121
	v_exp_f32_e32 v155, v2
	v_fma_f32 v2, v30, s0, -v121
; #define LAS __attribute__((address_space(3)))
; template <class ScoreFn>
; __device__ __forceinline__ void attn_step(AttnState& st, const bf16x8 (&qf)[4], LAS unsigned char* kb, LAS unsigned char* vb, int lane, const ScoreFn& sf) {
;     ...
;     LAS unsigned char* kp = kb + r * KVP; const int kx = (h ^ (r & 7)) << 4;
; #pragma unroll
;     for (int ds = 0; ds < 4; ++ds) {
;         const bf16x8 k0 = *(const LAS bf16x8*)(kp + (kx ^ (ds << 5))), k1 = *(const LAS bf16x8*)(kp + 32 * KVP + (kx ^ (ds << 5)));
;         s0 = MFMA32(k0, qf[ds], s0); s1 = MFMA32(k1, qf[ds], s1);
;     ...
;     for (int i = 0; i < 16; ++i) { s0[i] = __builtin_amdgcn_exp2f(s0[i] - mn); s1[i] = __builtin_amdgcn_exp2f(s1[i] - mn); ps += s0[i] + s1[i]; }
;     st.l = st.l * alpha + ps; st.m = mn;
; #pragma unroll
;     for (int i = 0; i < 16; ++i) { st.o0[i] *= alpha; st.o1[i] *= alpha; }
;     __builtin_amdgcn_sched_barrier(0);
;     v4u pw[4];
;     pw[0].x = cvtpk(s0[0], s0[1]); pw[0].y = cvtpk(s0[2], s0[3]); pw[0].z = cvtpk(s0[4], s0[5]); pw[0].w = cvtpk(s0[6], s0[7]);
;     pw[1].x = cvtpk(s0[8], s0[9]); pw[1].y = cvtpk(s0[10], s0[11]); pw[1].z = cvtpk(s0[12], s0[13]); pw[1].w = cvtpk(s0[14], s0[15]);
;     pw[2].x = cvtpk(s1[0], s1[1]); pw[2].y = cvtpk(s1[2], s1[3]); pw[2].z = cvtpk(s1[4], s1[5]); pw[2].w = cvtpk(s1[6], s1[7]);
;     pw[3].x = cvtpk(s1[8], s1[9]); pw[3].y = cvtpk(s1[10], s1[11]); pw[3].z = cvtpk(s1[12], s1[13]); pw[3].w = cvtpk(s1[14], s1[15]);
;     const int i16 = lane & 15, q = i16 >> 2, p = i16 & 3, dhalf = (lane >> 4) & 1;
;     LAS unsigned char* vrow = vb + (4 * h + q) * KVP + (p & 1) * 8;
;     LAS unsigned char* vp0 = vrow + (((2 * dhalf + (p >> 1)) ^ (4 * h + q)) << 4); LAS unsigned char* vp1 = vrow + (((4 + 2 * dhalf + (p >> 1)) ^ (4 * h + q)) << 4);
; #pragma unroll
;     for (int ks = 0; ks < 4; ++ks) {
;         const s16x4 l0 = tr_read(vp0 + (16 * ks) * KVP), h0 = tr_read(vp0 + (16 * ks + 8) * KVP);
;         const s16x4 l1 = tr_read(vp1 + (16 * ks) * KVP), h1 = tr_read(vp1 + (16 * ks + 8) * KVP);
;         const bf16x8 v0 = (bf16x8){l0[0], l0[1], l0[2], l0[3], h0[0], h0[1], h0[2], h0[3]};
;         const bf16x8 v1 = (bf16x8){l1[0], l1[1], l1[2], l1[3], h1[0], h1[1], h1[2], h1[3]};
;         const bf16x8 pf = __builtin_bit_cast(bf16x8, pw[ks]);
;         st.o0 = MFMA32(v0, pf, st.o0); st.o1 = MFMA32(v1, pf, st.o1);
;     }
	v_exp_f32_e32 v157, v2
	v_fma_f32 v2, v15, s0, -v121
	v_exp_f32_e32 v158, v2
	v_fma_f32 v2, v31, s0, -v121
	v_exp_f32_e32 v160, v2
	v_add_f32_e32 v161, v157, v155
	v_pk_add_f32 v[2:3], v[160:161], v[158:159]
	s_nop 0
	v_pk_add_f32 v[162:163], v[2:3], v[2:3] op_sel_hi:[0,1]
	v_fma_f32 v2, v16, s0, -v121
	v_exp_f32_e32 v159, v2
	v_fma_f32 v2, v32, s0, -v121
	v_exp_f32_e32 v161, v2
	v_fma_f32 v2, v17, s0, -v121
	v_exp_f32_e32 v162, v2
	v_fma_f32 v2, v33, s0, -v121
	v_exp_f32_e32 v166, v2
	v_sub_f32_e32 v2, v110, v121
	v_exp_f32_e32 v18, v2
	v_add_f32_e32 v167, v161, v159
	v_pk_add_f32 v[2:3], v[166:167], v[162:163]
	v_pk_mul_f32 v[16:17], v[80:81], v[18:19] op_sel_hi:[1,0]
	v_add_f32_e32 v129, v2, v3
	v_fmac_f32_e32 v129, v109, v18
	v_pk_mul_f32 v[14:15], v[76:77], v[18:19] op_sel_hi:[1,0]
	v_pk_mul_f32 v[12:13], v[72:73], v[18:19] op_sel_hi:[1,0]
	v_pk_mul_f32 v[10:11], v[68:69], v[18:19] op_sel_hi:[1,0]
	v_pk_mul_f32 v[8:9], v[62:63], v[18:19] op_sel_hi:[1,0]
	v_pk_mul_f32 v[6:7], v[58:59], v[18:19] op_sel_hi:[1,0]
	v_pk_mul_f32 v[4:5], v[54:55], v[18:19] op_sel_hi:[1,0]
	v_pk_mul_f32 v[2:3], v[84:85], v[18:19] op_sel_hi:[1,0]
	v_pk_mul_f32 v[32:33], v[78:79], v[18:19] op_sel_hi:[1,0]
	v_pk_mul_f32 v[30:31], v[74:75], v[18:19] op_sel_hi:[1,0]
	v_pk_mul_f32 v[28:29], v[70:71], v[18:19] op_sel_hi:[1,0]
	v_pk_mul_f32 v[26:27], v[64:65], v[18:19] op_sel_hi:[1,0]
	v_pk_mul_f32 v[24:25], v[60:61], v[18:19] op_sel_hi:[1,0]
	v_pk_mul_f32 v[22:23], v[56:57], v[18:19] op_sel_hi:[1,0]
	v_pk_mul_f32 v[20:21], v[52:53], v[18:19] op_sel_hi:[1,0]
	v_pk_mul_f32 v[18:19], v[82:83], v[18:19] op_sel_hi:[1,0]
	v_cvt_pk_bf16_f32 v135, v135, v136
	v_cvt_pk_bf16_f32 v136, v137, v138
	v_cvt_pk_bf16_f32 v137, v139, v140
	v_cvt_pk_bf16_f32 v138, v141, v150
	v_cvt_pk_bf16_f32 v139, v151, v154
	v_cvt_pk_bf16_f32 v140, v155, v158
	v_cvt_pk_bf16_f32 v143, v143, v144
	v_cvt_pk_bf16_f32 v144, v145, v146
	v_cvt_pk_bf16_f32 v145, v147, v148
	v_cvt_pk_bf16_f32 v146, v149, v152
	v_cvt_pk_bf16_f32 v147, v153, v156
	v_cvt_pk_bf16_f32 v148, v157, v160
	ds_read_b64_tr_b16 v[150:151], v126
	ds_read_b64_tr_b16 v[152:153], v127
	ds_read_b64_tr_b16 v[154:155], v125
	ds_read_b64_tr_b16 v[156:157], v124
	v_cvt_pk_bf16_f32 v134, v133, v66
	v_cvt_pk_bf16_f32 v141, v159, v162
	v_cvt_pk_bf16_f32 v142, v165, v142
	s_waitcnt lgkmcnt(2)
	v_mfma_f32_32x32x16_bf16 v[2:17], v[150:153], v[134:137], v[2:17]
	v_cvt_pk_bf16_f32 v149, v161, v166
	s_mov_b64 s[8:9], 0
	s_waitcnt lgkmcnt(0)
	v_mfma_f32_32x32x16_bf16 v[18:33], v[154:157], v[134:137], v[18:33]
	ds_read_b64_tr_b16 v[134:135], v122
	ds_read_b64_tr_b16 v[136:137], v123
	ds_read_b64_tr_b16 v[150:151], v119
	ds_read_b64_tr_b16 v[152:153], v120
	s_waitcnt lgkmcnt(2)
	v_mfma_f32_32x32x16_bf16 v[2:17], v[134:137], v[138:141], v[2:17]
	s_waitcnt lgkmcnt(0)
	v_mfma_f32_32x32x16_bf16 v[18:33], v[150:153], v[138:141], v[18:33]
	ds_read_b64_tr_b16 v[134:135], v117
	ds_read_b64_tr_b16 v[136:137], v118
	ds_read_b64_tr_b16 v[138:139], v115
	ds_read_b64_tr_b16 v[140:141], v116
	s_waitcnt lgkmcnt(2)
	v_mfma_f32_32x32x16_bf16 v[2:17], v[134:137], v[142:145], v[2:17]
	s_waitcnt lgkmcnt(0)
	v_mfma_f32_32x32x16_bf16 v[18:33], v[138:141], v[142:145], v[18:33]
	ds_read_b64_tr_b16 v[134:135], v113
	ds_read_b64_tr_b16 v[136:137], v114
	ds_read_b64_tr_b16 v[138:139], v111
	ds_read_b64_tr_b16 v[140:141], v112
	s_waitcnt lgkmcnt(2)
	v_mfma_f32_32x32x16_bf16 v[2:17], v[134:137], v[146:149], v[2:17]
	s_waitcnt lgkmcnt(0)
	v_mfma_f32_32x32x16_bf16 v[18:33], v[138:141], v[146:149], v[18:33]
.LBB0_583:
	s_andn2_b64 vcc, exec, s[8:9]
	s_cbranch_vccnz .LBB0_585
	s_mov_b32 s1, 0
	v_mov_b32_e32 v66, s14
	s_nop 5
	v_add_u32_e32 v6, s1, v132
	ds_read_b128 v[2:5], v6
	v_add_u32_e32 v10, s1, v131
	v_add_u32_e32 v11, s1, v130
	ds_read_b128 v[130:133], v10 offset:4096
	ds_read_b128 v[6:9], v6 offset:4096
	s_waitcnt lgkmcnt(0)
	v_mfma_f32_32x32x16_bf16 v[18:33], v[2:5], v[34:37], 0
	ds_read_b128 v[2:5], v10
	v_add_u32_e32 v10, s1, v128
	ds_read_b128 v[134:137], v11 offset:4096
	s_waitcnt lgkmcnt(0)
	v_mfma_f32_32x32x16_bf16 v[18:33], v[2:5], v[38:41], v[18:33]
	ds_read_b128 v[2:5], v11
	s_waitcnt lgkmcnt(0)
	v_mfma_f32_32x32x16_bf16 v[18:33], v[2:5], v[42:45], v[18:33]
	ds_read_b128 v[2:5], v10
	ds_read_b128 v[138:141], v10 offset:4096
	s_waitcnt lgkmcnt(0)
; #define MFMA32(a, b, c) __builtin_amdgcn_mfma_f32_32x32x16_bf16((a), (b), (c), 0, 0, 0)
; template <class ScoreFn>
; __device__ __forceinline__ void attn_step(AttnState& st, const bf16x8 (&qf)[4], LAS unsigned char* kb, LAS unsigned char* vb, int lane, const ScoreFn& sf) {
;     ...
;         s0 = MFMA32(k0, qf[ds], s0); s1 = MFMA32(k1, qf[ds], s1);
;     }
;     float mt = NEG_BIG;
;     __builtin_amdgcn_sched_barrier(0);
; #pragma unroll
;     for (int i = 0; i < 16; ++i) { s0[i] = sf(s0[i], (i & 3) + 8 * (i >> 2), h, r); mt = fmaxf(mt, s0[i]); if ((i & 7) == 7) __builtin_amdgcn_sched_barrier(0); }
; #pragma unroll
;     for (int i = 0; i < 16; ++i) { s1[i] = sf(s1[i], 32 + (i & 3) + 8 * (i >> 2), h, r); mt = fmaxf(mt, s1[i]); if ((i & 7) == 7) __builtin_amdgcn_sched_barrier(0); }
	v_mfma_f32_32x32x16_bf16 v[18:33], v[2:5], v[46:49], v[18:33]
	v_mfma_f32_32x32x16_bf16 v[2:17], v[6:9], v[34:37], 0
	v_mfma_f32_32x32x16_bf16 v[2:17], v[130:133], v[38:41], v[2:17]
	v_mfma_f32_32x32x16_bf16 v[2:17], v[134:137], v[42:45], v[2:17]
	v_mfma_f32_32x32x16_bf16 v[2:17], v[138:141], v[46:49], v[2:17]
	v_add_u32_e32 v121, v86, v66
	s_nop 6
	v_mul_f32_e32 v18, 0x3e38aa3b, v18
	v_cmp_gt_u32_e32 vcc, s17, v121
	v_add_u32_e32 v128, 1, v121
	v_mul_f32_e32 v19, 0x3e38aa3b, v19
	v_cndmask_b32_e32 v18, v250, v18, vcc
	v_cmp_gt_u32_e32 vcc, s17, v128
	v_add_u32_e32 v129, 2, v121
	v_mul_f32_e32 v20, 0x3e38aa3b, v20
	v_cndmask_b32_e32 v19, v250, v19, vcc
	v_cmp_gt_u32_e32 vcc, s17, v129
	v_add_u32_e32 v129, 3, v121
	v_mul_f32_e32 v21, 0x3e38aa3b, v21
	v_cndmask_b32_e32 v20, v250, v20, vcc
	v_cmp_gt_u32_e32 vcc, s17, v129
	v_add_u32_e32 v129, 8, v121
	v_mul_f32_e32 v22, 0x3e38aa3b, v22
	v_cndmask_b32_e32 v21, v250, v21, vcc
	v_cmp_gt_u32_e32 vcc, s17, v129
	v_add_u32_e32 v129, 9, v121
	v_mul_f32_e32 v23, 0x3e38aa3b, v23
	v_cndmask_b32_e32 v22, v250, v22, vcc
	v_cmp_gt_u32_e32 vcc, s17, v129
	v_add_u32_e32 v129, 10, v121
	v_mul_f32_e32 v24, 0x3e38aa3b, v24
	v_cndmask_b32_e32 v23, v250, v23, vcc
	v_cmp_gt_u32_e32 vcc, s17, v129
	v_add_u32_e32 v129, 11, v121
	v_mul_f32_e32 v25, 0x3e38aa3b, v25
	v_cndmask_b32_e32 v24, v250, v24, vcc
	v_cmp_gt_u32_e32 vcc, s17, v129
	v_add_u32_e32 v129, 16, v121
	v_mul_f32_e32 v26, 0x3e38aa3b, v26
	v_cndmask_b32_e32 v25, v250, v25, vcc
	v_cmp_gt_u32_e32 vcc, s17, v129
	v_add_u32_e32 v129, 17, v121
	s_mov_b32 s1, 0xf149f2ca
	v_cndmask_b32_e32 v26, v250, v26, vcc
	v_mul_f32_e32 v27, 0x3e38aa3b, v27
	v_cmp_gt_u32_e32 vcc, s17, v129
	v_add_u32_e32 v129, 18, v121
	v_max3_f32 v128, v18, s1, v19
	v_cndmask_b32_e32 v27, v250, v27, vcc
	v_mul_f32_e32 v28, 0x3e38aa3b, v28
	v_cmp_gt_u32_e32 vcc, s17, v129
	v_add_u32_e32 v129, 19, v121
	v_max3_f32 v128, v128, v20, v21
	v_cndmask_b32_e32 v28, v250, v28, vcc
	v_mul_f32_e32 v29, 0x3e38aa3b, v29
	v_cmp_gt_u32_e32 vcc, s17, v129
	v_add_u32_e32 v129, 24, v121
	v_max3_f32 v128, v128, v22, v23
	v_cndmask_b32_e32 v29, v250, v29, vcc
	v_mul_f32_e32 v30, 0x3e38aa3b, v30
	v_cmp_gt_u32_e32 vcc, s17, v129
	v_add_u32_e32 v129, 25, v121
	v_max3_f32 v128, v128, v24, v25
	v_cndmask_b32_e32 v30, v250, v30, vcc
	v_mul_f32_e32 v31, 0x3e38aa3b, v31
	v_cmp_gt_u32_e32 vcc, s17, v129
	v_add_u32_e32 v129, 26, v121
	v_max3_f32 v128, v128, v26, v27
	v_cndmask_b32_e32 v31, v250, v31, vcc
	v_mul_f32_e32 v32, 0x3e38aa3b, v32
	v_cmp_gt_u32_e32 vcc, s17, v129
	v_add_u32_e32 v121, 27, v121
	v_max3_f32 v128, v128, v28, v29
	v_cndmask_b32_e32 v32, v250, v32, vcc
	v_mul_f32_e32 v33, 0x3e38aa3b, v33
	v_cmp_gt_u32_e32 vcc, s17, v121
	v_max3_f32 v128, v128, v30, v31
	v_add_u32_e32 v66, v87, v66
	v_cndmask_b32_e32 v33, v250, v33, vcc
	v_max3_f32 v121, v128, v32, v33
	v_mul_f32_e32 v2, 0x3e38aa3b, v2
	v_cmp_gt_u32_e32 vcc, s17, v66
	v_add_u32_e32 v128, 1, v66
	v_mul_f32_e32 v3, 0x3e38aa3b, v3
	v_cndmask_b32_e32 v2, v250, v2, vcc
	v_cmp_gt_u32_e32 vcc, s17, v128
	v_add_u32_e32 v128, 2, v66
	v_mul_f32_e32 v4, 0x3e38aa3b, v4
	v_cndmask_b32_e32 v3, v250, v3, vcc
	v_cmp_gt_u32_e32 vcc, s17, v128
	v_add_u32_e32 v128, 3, v66
	v_mul_f32_e32 v5, 0x3e38aa3b, v5
	v_cndmask_b32_e32 v4, v250, v4, vcc
	v_cmp_gt_u32_e32 vcc, s17, v128
	v_add_u32_e32 v128, 8, v66
	v_mul_f32_e32 v6, 0x3e38aa3b, v6
	v_cndmask_b32_e32 v5, v250, v5, vcc
	v_cmp_gt_u32_e32 vcc, s17, v128
	v_add_u32_e32 v128, 9, v66
	v_mul_f32_e32 v7, 0x3e38aa3b, v7
	v_cndmask_b32_e32 v6, v250, v6, vcc
	v_cmp_gt_u32_e32 vcc, s17, v128
	v_add_u32_e32 v128, 10, v66
	v_mul_f32_e32 v8, 0x3e38aa3b, v8
	v_cndmask_b32_e32 v7, v250, v7, vcc
	v_cmp_gt_u32_e32 vcc, s17, v128
	v_add_u32_e32 v128, 11, v66
	v_mul_f32_e32 v9, 0x3e38aa3b, v9
	v_cndmask_b32_e32 v8, v250, v8, vcc
	v_cmp_gt_u32_e32 vcc, s17, v128
	v_add_u32_e32 v128, 16, v66
	v_mul_f32_e32 v10, 0x3e38aa3b, v10
	v_cndmask_b32_e32 v9, v250, v9, vcc
	v_cmp_gt_u32_e32 vcc, s17, v128
	v_add_u32_e32 v128, 17, v66
	v_mul_f32_e32 v11, 0x3e38aa3b, v11
	v_cndmask_b32_e32 v10, v250, v10, vcc
	v_cmp_gt_u32_e32 vcc, s17, v128
	v_add_u32_e32 v128, 18, v66
	v_max3_f32 v121, v121, v2, v3
	v_cndmask_b32_e32 v11, v250, v11, vcc
	v_mul_f32_e32 v12, 0x3e38aa3b, v12
	v_cmp_gt_u32_e32 vcc, s17, v128
	v_add_u32_e32 v128, 19, v66
	v_max3_f32 v121, v121, v4, v5
	v_cndmask_b32_e32 v12, v250, v12, vcc
	v_mul_f32_e32 v13, 0x3e38aa3b, v13
	v_cmp_gt_u32_e32 vcc, s17, v128
	v_add_u32_e32 v128, 24, v66
	v_max3_f32 v121, v121, v6, v7
	v_cndmask_b32_e32 v13, v250, v13, vcc
	v_mul_f32_e32 v14, 0x3e38aa3b, v14
	v_cmp_gt_u32_e32 vcc, s17, v128
	v_add_u32_e32 v128, 25, v66
	v_max3_f32 v121, v121, v8, v9
	v_cndmask_b32_e32 v14, v250, v14, vcc
	v_mul_f32_e32 v15, 0x3e38aa3b, v15
	v_cmp_gt_u32_e32 vcc, s17, v128
	v_add_u32_e32 v128, 26, v66
	v_max3_f32 v121, v121, v10, v11
	v_cndmask_b32_e32 v15, v250, v15, vcc
	v_mul_f32_e32 v16, 0x3e38aa3b, v16
	v_cmp_gt_u32_e32 vcc, s17, v128
	v_add_u32_e32 v66, 27, v66
	v_max3_f32 v121, v121, v12, v13
	v_cndmask_b32_e32 v16, v250, v16, vcc
	v_mul_f32_e32 v17, 0x3e38aa3b, v17
	v_cmp_gt_u32_e32 vcc, s17, v66
	v_max3_f32 v121, v121, v14, v15
	s_nop 0
	v_cndmask_b32_e32 v17, v250, v17, vcc
	v_cmp_lt_i32_e32 vcc, v242, v241
	v_max3_f32 v66, v121, v16, v17
	s_nop 0
	v_cndmask_b32_e32 v121, v240, v242, vcc
	v_lshlrev_b32_e32 v121, 2, v121
	ds_bpermute_b32 v121, v121, v66
	s_waitcnt lgkmcnt(0)
; #define LAS __attribute__((address_space(3)))
; #define MFMA32(a, b, c) __builtin_amdgcn_mfma_f32_32x32x16_bf16((a), (b), (c), 0, 0, 0)
; __device__ __forceinline__ unsigned cvtpk(float lo, float hi) { return pg8::cvt_pk_bf16(lo, hi); }
; template <class ScoreFn>
; __device__ __forceinline__ void attn_step(AttnState& st, const bf16x8 (&qf)[4], LAS unsigned char* kb, LAS unsigned char* vb, int lane, const ScoreFn& sf) {
;     ...
;     mt = fmaxf(mt, __shfl_xor(mt, 32));
;     const float mn = fmaxf(st.m, mt), alpha = __builtin_amdgcn_exp2f(st.m - mn);
;     float ps = 0.f;
; #pragma unroll
;     for (int i = 0; i < 16; ++i) { s0[i] = __builtin_amdgcn_exp2f(s0[i] - mn); s1[i] = __builtin_amdgcn_exp2f(s1[i] - mn); ps += s0[i] + s1[i]; }
;     st.l = st.l * alpha + ps; st.m = mn;
; #pragma unroll
;     for (int i = 0; i < 16; ++i) { st.o0[i] *= alpha; st.o1[i] *= alpha; }
;     __builtin_amdgcn_sched_barrier(0);
;     v4u pw[4];
;     pw[0].x = cvtpk(s0[0], s0[1]); pw[0].y = cvtpk(s0[2], s0[3]); pw[0].z = cvtpk(s0[4], s0[5]); pw[0].w = cvtpk(s0[6], s0[7]);
;     pw[1].x = cvtpk(s0[8], s0[9]); pw[1].y = cvtpk(s0[10], s0[11]); pw[1].z = cvtpk(s0[12], s0[13]); pw[1].w = cvtpk(s0[14], s0[15]);
;     pw[2].x = cvtpk(s1[0], s1[1]); pw[2].y = cvtpk(s1[2], s1[3]); pw[2].z = cvtpk(s1[4], s1[5]); pw[2].w = cvtpk(s1[6], s1[7]);
;     pw[3].x = cvtpk(s1[8], s1[9]); pw[3].y = cvtpk(s1[10], s1[11]); pw[3].z = cvtpk(s1[12], s1[13]); pw[3].w = cvtpk(s1[14], s1[15]);
;     const int i16 = lane & 15, q = i16 >> 2, p = i16 & 3, dhalf = (lane >> 4) & 1;
;     LAS unsigned char* vrow = vb + (4 * h + q) * KVP + (p & 1) * 8;
;     LAS unsigned char* vp0 = vrow + (((2 * dhalf + (p >> 1)) ^ (4 * h + q)) << 4); LAS unsigned char* vp1 = vrow + (((4 + 2 * dhalf + (p >> 1)) ^ (4 * h + q)) << 4);
; #pragma unroll
;     for (int ks = 0; ks < 4; ++ks) {
;         const s16x4 l0 = tr_read(vp0 + (16 * ks) * KVP), h0 = tr_read(vp0 + (16 * ks + 8) * KVP);
;         const s16x4 l1 = tr_read(vp1 + (16 * ks) * KVP), h1 = tr_read(vp1 + (16 * ks + 8) * KVP);
;         const bf16x8 v0 = (bf16x8){l0[0], l0[1], l0[2], l0[3], h0[0], h0[1], h0[2], h0[3]};
;         const bf16x8 v1 = (bf16x8){l1[0], l1[1], l1[2], l1[3], h1[0], h1[1], h1[2], h1[3]};
;         const bf16x8 pf = __builtin_bit_cast(bf16x8, pw[ks]);
;         st.o0 = MFMA32(v0, pf, st.o0); st.o1 = MFMA32(v1, pf, st.o1);
;     }
	v_max3_f32 v121, v110, v66, v121
	v_sub_f32_e32 v2, v2, v121
	v_sub_f32_e32 v18, v18, v121
	v_exp_f32_e32 v159, v2
	v_sub_f32_e32 v2, v19, v121
	v_exp_f32_e32 v158, v18
	v_exp_f32_e32 v66, v2
	v_sub_f32_e32 v2, v3, v121
	v_exp_f32_e32 v128, v2
	v_add_f32_e32 v129, v159, v158
	v_pk_add_f32 v[2:3], v[128:129], v[66:67]
	s_nop 0
	v_pk_add_f32 v[130:131], v[2:3], v[2:3] op_sel_hi:[0,1]
	v_sub_f32_e32 v2, v20, v121
	v_exp_f32_e32 v160, v2
	v_sub_f32_e32 v2, v4, v121
	v_exp_f32_e32 v161, v2
	v_sub_f32_e32 v2, v21, v121
	v_exp_f32_e32 v130, v2
	v_sub_f32_e32 v2, v5, v121
	v_exp_f32_e32 v132, v2
	v_add_f32_e32 v133, v161, v160
	v_pk_add_f32 v[2:3], v[132:133], v[130:131]
	s_nop 0
	v_pk_add_f32 v[134:135], v[2:3], v[2:3] op_sel_hi:[0,1]
	v_sub_f32_e32 v2, v22, v121
	v_exp_f32_e32 v131, v2
	v_sub_f32_e32 v2, v6, v121
	v_exp_f32_e32 v133, v2
	v_sub_f32_e32 v2, v23, v121
	v_exp_f32_e32 v134, v2
	v_sub_f32_e32 v2, v7, v121
	v_exp_f32_e32 v136, v2
	v_add_f32_e32 v137, v133, v131
	v_pk_add_f32 v[2:3], v[136:137], v[134:135]
	s_nop 0
	v_pk_add_f32 v[138:139], v[2:3], v[2:3] op_sel_hi:[0,1]
	v_sub_f32_e32 v2, v24, v121
	v_exp_f32_e32 v135, v2
	v_sub_f32_e32 v2, v8, v121
	v_exp_f32_e32 v137, v2
	v_sub_f32_e32 v2, v25, v121
	v_exp_f32_e32 v138, v2
	v_sub_f32_e32 v2, v9, v121
	v_exp_f32_e32 v140, v2
	v_add_f32_e32 v141, v137, v135
	v_pk_add_f32 v[2:3], v[140:141], v[138:139]
	s_nop 0
	v_pk_add_f32 v[142:143], v[2:3], v[2:3] op_sel_hi:[0,1]
	v_sub_f32_e32 v2, v26, v121
	v_exp_f32_e32 v139, v2
	v_sub_f32_e32 v2, v10, v121
	v_exp_f32_e32 v141, v2
	v_sub_f32_e32 v2, v27, v121
	v_exp_f32_e32 v142, v2
	v_sub_f32_e32 v2, v11, v121
	v_exp_f32_e32 v144, v2
	v_add_f32_e32 v145, v141, v139
	v_pk_add_f32 v[2:3], v[144:145], v[142:143]
	s_nop 0
	v_pk_add_f32 v[146:147], v[2:3], v[2:3] op_sel_hi:[0,1]
	v_sub_f32_e32 v2, v28, v121
	v_exp_f32_e32 v143, v2
	v_sub_f32_e32 v2, v12, v121
	v_exp_f32_e32 v145, v2
	v_sub_f32_e32 v2, v29, v121
	v_exp_f32_e32 v146, v2
	v_sub_f32_e32 v2, v13, v121
	v_exp_f32_e32 v148, v2
	v_add_f32_e32 v149, v145, v143
	v_pk_add_f32 v[2:3], v[148:149], v[146:147]
	s_nop 0
	v_pk_add_f32 v[150:151], v[2:3], v[2:3] op_sel_hi:[0,1]
	v_sub_f32_e32 v2, v30, v121
	v_exp_f32_e32 v147, v2
	v_sub_f32_e32 v2, v14, v121
	v_exp_f32_e32 v149, v2
	v_sub_f32_e32 v2, v31, v121
	v_exp_f32_e32 v150, v2
	v_sub_f32_e32 v2, v15, v121
	v_exp_f32_e32 v152, v2
	v_add_f32_e32 v153, v149, v147
	v_pk_add_f32 v[2:3], v[152:153], v[150:151]
	s_nop 0
	v_pk_add_f32 v[154:155], v[2:3], v[2:3] op_sel_hi:[0,1]
	v_sub_f32_e32 v2, v32, v121
	v_exp_f32_e32 v151, v2
	v_sub_f32_e32 v2, v16, v121
	v_exp_f32_e32 v153, v2
	v_sub_f32_e32 v2, v33, v121
	v_exp_f32_e32 v154, v2
	v_sub_f32_e32 v2, v17, v121
	v_exp_f32_e32 v156, v2
	v_sub_f32_e32 v2, v110, v121
	v_exp_f32_e32 v18, v2
	v_add_f32_e32 v157, v153, v151
	v_pk_add_f32 v[2:3], v[156:157], v[154:155]
	v_pk_mul_f32 v[16:17], v[80:81], v[18:19] op_sel_hi:[1,0]
	v_add_f32_e32 v129, v2, v3
	v_fmac_f32_e32 v129, v109, v18
	v_pk_mul_f32 v[14:15], v[76:77], v[18:19] op_sel_hi:[1,0]
	v_pk_mul_f32 v[12:13], v[72:73], v[18:19] op_sel_hi:[1,0]
	v_pk_mul_f32 v[10:11], v[68:69], v[18:19] op_sel_hi:[1,0]
	v_pk_mul_f32 v[8:9], v[62:63], v[18:19] op_sel_hi:[1,0]
	v_pk_mul_f32 v[6:7], v[58:59], v[18:19] op_sel_hi:[1,0]
	v_pk_mul_f32 v[4:5], v[54:55], v[18:19] op_sel_hi:[1,0]
	v_pk_mul_f32 v[2:3], v[84:85], v[18:19] op_sel_hi:[1,0]
	v_pk_mul_f32 v[32:33], v[78:79], v[18:19] op_sel_hi:[1,0]
	v_pk_mul_f32 v[30:31], v[74:75], v[18:19] op_sel_hi:[1,0]
	v_pk_mul_f32 v[28:29], v[70:71], v[18:19] op_sel_hi:[1,0]
	v_pk_mul_f32 v[26:27], v[64:65], v[18:19] op_sel_hi:[1,0]
	v_pk_mul_f32 v[24:25], v[60:61], v[18:19] op_sel_hi:[1,0]
	v_pk_mul_f32 v[22:23], v[56:57], v[18:19] op_sel_hi:[1,0]
	v_pk_mul_f32 v[20:21], v[52:53], v[18:19] op_sel_hi:[1,0]
	v_pk_mul_f32 v[18:19], v[82:83], v[18:19] op_sel_hi:[1,0]
	ds_read_b64_tr_b16 v[72:73], v126
	ds_read_b64_tr_b16 v[74:75], v127
	ds_read_b64_tr_b16 v[76:77], v125
	ds_read_b64_tr_b16 v[78:79], v124
	v_cvt_pk_bf16_f32 v52, v158, v66
	v_cvt_pk_bf16_f32 v53, v160, v130
	v_cvt_pk_bf16_f32 v54, v131, v134
	v_cvt_pk_bf16_f32 v55, v135, v138
	v_cvt_pk_bf16_f32 v56, v139, v142
	v_cvt_pk_bf16_f32 v57, v143, v146
	s_waitcnt lgkmcnt(2)
	v_mfma_f32_32x32x16_bf16 v[2:17], v[72:75], v[52:55], v[2:17]
	v_cvt_pk_bf16_f32 v58, v147, v150
	v_cvt_pk_bf16_f32 v59, v151, v154
	v_cvt_pk_bf16_f32 v60, v159, v128
	v_cvt_pk_bf16_f32 v61, v161, v132
	v_cvt_pk_bf16_f32 v62, v133, v136
	v_cvt_pk_bf16_f32 v63, v137, v140
	v_cvt_pk_bf16_f32 v68, v141, v144
	s_waitcnt lgkmcnt(0)
	v_mfma_f32_32x32x16_bf16 v[18:33], v[76:79], v[52:55], v[18:33]
	ds_read_b64_tr_b16 v[52:53], v122
	ds_read_b64_tr_b16 v[54:55], v123
	ds_read_b64_tr_b16 v[72:73], v119
	ds_read_b64_tr_b16 v[74:75], v120
	v_cvt_pk_bf16_f32 v69, v145, v148
	v_cvt_pk_bf16_f32 v70, v149, v152
	v_cvt_pk_bf16_f32 v71, v153, v156
	s_waitcnt lgkmcnt(2)
	v_mfma_f32_32x32x16_bf16 v[2:17], v[52:55], v[56:59], v[2:17]
	s_waitcnt lgkmcnt(0)
	v_mfma_f32_32x32x16_bf16 v[18:33], v[72:75], v[56:59], v[18:33]
	ds_read_b64_tr_b16 v[52:53], v117
	ds_read_b64_tr_b16 v[54:55], v118
	ds_read_b64_tr_b16 v[56:57], v115
	ds_read_b64_tr_b16 v[58:59], v116
	s_waitcnt lgkmcnt(2)
	v_mfma_f32_32x32x16_bf16 v[2:17], v[52:55], v[60:63], v[2:17]
	s_waitcnt lgkmcnt(0)
	v_mfma_f32_32x32x16_bf16 v[18:33], v[56:59], v[60:63], v[18:33]
	ds_read_b64_tr_b16 v[52:53], v113
	ds_read_b64_tr_b16 v[54:55], v114
	ds_read_b64_tr_b16 v[56:57], v111
	ds_read_b64_tr_b16 v[58:59], v112
	s_waitcnt lgkmcnt(2)
	v_mfma_f32_32x32x16_bf16 v[2:17], v[52:55], v[68:71], v[2:17]
	s_waitcnt lgkmcnt(0)
	v_mfma_f32_32x32x16_bf16 v[18:33], v[56:59], v[68:71], v[18:33]

; #define LAS __attribute__((address_space(3)))
; #define MFMA32(a, b, c) __builtin_amdgcn_mfma_f32_32x32x16_bf16((a), (b), (c), 0, 0, 0)
; #define WG_BAR() do { asm volatile("s_waitcnt lgkmcnt(0)" ::: "memory"); __builtin_amdgcn_s_barrier(); asm volatile("" ::: "memory"); } while (0)
; template <class ScoreFn>
; __device__ __forceinline__ void attn_step(AttnState& st, const bf16x8 (&qf)[4], LAS unsigned char* kb, LAS unsigned char* vb, int lane, const ScoreFn& sf) {
;     ...
;     LAS unsigned char* kp = kb + r * KVP; const int kx = (h ^ (r & 7)) << 4;
; #pragma unroll
;     for (int ds = 0; ds < 4; ++ds) {
;         const bf16x8 k0 = *(const LAS bf16x8*)(kp + (kx ^ (ds << 5))), k1 = *(const LAS bf16x8*)(kp + 32 * KVP + (kx ^ (ds << 5)));
;         s0 = MFMA32(k0, qf[ds], s0); s1 = MFMA32(k1, qf[ds], s1);
;     }
;     float mt = NEG_BIG;
;     __builtin_amdgcn_sched_barrier(0);
; #pragma unroll
;     for (int i = 0; i < 16; ++i) { s0[i] = sf(s0[i], (i & 3) + 8 * (i >> 2), h, r); mt = fmaxf(mt, s0[i]); if ((i & 7) == 7) __builtin_amdgcn_sched_barrier(0); }
; #pragma unroll
;     for (int i = 0; i < 16; ++i) { s1[i] = sf(s1[i], 32 + (i & 3) + 8 * (i >> 2), h, r); mt = fmaxf(mt, s1[i]); if ((i & 7) == 7) __builtin_amdgcn_sched_barrier(0); }
;     mt = fmaxf(mt, __shfl_xor(mt, 32));
;     const float mn = fmaxf(st.m, mt), alpha = __builtin_amdgcn_exp2f(st.m - mn);
;     float ps = 0.f;
; #pragma unroll
;     for (int i = 0; i < 16; ++i) { s0[i] = __builtin_amdgcn_exp2f(s0[i] - mn); s1[i] = __builtin_amdgcn_exp2f(s1[i] - mn); ps += s0[i] + s1[i]; }
; template <bool ISB>
; __device__ __forceinline__ void attn_wg_item(Frame& F, int l, int idx) {
;     ...
;     AttnState st;
; #pragma unroll
;     for (int i = 0; i < 16; ++i) { st.o0[i] = 0.f; st.o1[i] = 0.f; }
;     st.m = NEG_BIG; st.l = 0.f;
; #pragma unroll
;     for (int t = 0; t < ATT_D; ++t) ATT_DMA(t);
;     if (ISB && lat) {
;         const float* bsrc = KIN(I_NBBIAS) + (size_t)(l * 8 + (ix & 7)) * 465;
;         if (tid < 465) tab[64 + tid] = bsrc[tid] * LOG2E; }
;     for (int s = 0; s < NS; ++s) {
;         ATT_DMA(s + ATT_D);
;         asm volatile("s_waitcnt vmcnt(8)" ::: "memory");
;         WG_BAR();
;         LAS unsigned char* cur = ring + (s % ATT_NB) * KV_BUF;
;         if (s >= nloc) { ScorePlain sf; attn_step(st, qf, cur, cur + KV_TILE, lane, sf); }
.LBB0_618:
	s_mul_hi_u32 s1, s80, 0xaaaaaaab
	s_lshr_b32 s1, s1, 2
	s_mul_i32 s1, s1, 0x18000
	v_readlane_b32 s2, v253, 14
	s_sub_i32 s74, s2, s1
	v_readlane_b32 s2, v253, 16
	s_sub_i32 s1, s2, s1
	s_mul_hi_u32 s2, s82, 0xaaaaaaab
	s_lshr_b32 s2, s2, 2
	s_add_i32 s75, s82, 4
	s_mul_i32 s2, s2, 0x18000
	s_sub_i32 s2, s81, s2
	s_cmp_lt_i32 s82, s78
	v_add_u32_e32 v139, s2, v96
	v_add_u32_e32 v138, s2, v97
	v_add_u32_e32 v137, s2, v98
	v_add_u32_e32 v136, s2, v99
	v_add3_u32 v134, s2, v100, v101
	v_add3_u32 v133, s2, v102, v101
	v_add3_u32 v129, s2, v103, v101
	v_add3_u32 v128, s2, v104, v101
	v_add3_u32 v125, s2, v105, v101
	v_add3_u32 v124, s2, v106, v101
	v_add3_u32 v121, s2, v107, v101
	v_add3_u32 v120, s2, v108, v101
	v_add3_u32 v118, s2, v110, v101
	v_add3_u32 v119, s2, v111, v101
	v_add3_u32 v122, s2, v112, v101
	v_add3_u32 v123, s2, v113, v101
	v_add3_u32 v126, s2, v114, v101
	v_add3_u32 v127, s2, v115, v101
	v_add3_u32 v132, s2, v116, v101
	v_add3_u32 v135, s2, v117, v101
	s_cselect_b64 s[2:3], -1, 0
	s_and_b64 vcc, s[2:3], exec
	s_cselect_b32 s2, s75, s79
	s_cmp_lt_i32 s2, s78
	s_cselect_b32 s3, 0, s78
	s_cselect_b32 s75, s77, 0x2000
	s_sub_i32 s2, s2, s3
	s_lshl_b32 s2, s2, 6
	s_add_i32 s2, s2, s75
	s_add_i32 s3, s81, s74
	s_add_i32 m0, s3, 0
	v_mad_i64_i32 v[34:35], s[2:3], s2, v249, v[92:93]
	v_lshl_add_u64 v[36:37], v[34:35], 0, s[86:87]
	s_add_i32 s1, s81, s1
	global_load_lds_dwordx4 v[36:37], off
	v_lshl_add_u64 v[34:35], v[34:35], 0, s[96:97]
	s_add_i32 m0, s1, 0
	s_mov_b64 s[74:75], -1
	global_load_lds_dwordx4 v[34:35], off
	s_waitcnt vmcnt(8)
	s_waitcnt lgkmcnt(0)
	s_barrier
	s_cbranch_vccnz .LBB0_620
	s_mov_b32 s1, 0
	v_add_u32_e32 v38, s1, v139
	ds_read_b128 v[34:37], v38
	ds_read_b128 v[50:53], v38 offset:4096
	v_add_u32_e32 v58, s1, v138
	ds_read_b128 v[54:57], v58
	ds_read_b128 v[84:87], v58 offset:4096
	v_add_u32_e32 v59, s1, v137
	v_add_u32_e32 v58, s1, v136
	s_waitcnt lgkmcnt(0)
	v_mfma_f32_32x32x16_bf16 v[34:49], v[34:37], v[68:71], 0
	ds_read_b128 v[88:91], v59 offset:4096
	v_mfma_f32_32x32x16_bf16 v[34:49], v[54:57], v[72:75], v[34:49]
	ds_read_b128 v[54:57], v59
	s_waitcnt lgkmcnt(0)
	v_mfma_f32_32x32x16_bf16 v[34:49], v[54:57], v[76:79], v[34:49]
	ds_read_b128 v[54:57], v58
	ds_read_b128 v[140:143], v58 offset:4096
	s_waitcnt lgkmcnt(0)
	v_mfma_f32_32x32x16_bf16 v[34:49], v[54:57], v[80:83], v[34:49]
	v_mfma_f32_32x32x16_bf16 v[50:65], v[50:53], v[68:71], 0
	v_mfma_f32_32x32x16_bf16 v[50:65], v[84:87], v[72:75], v[50:65]
	v_mfma_f32_32x32x16_bf16 v[50:65], v[88:91], v[76:79], v[50:65]
	v_mfma_f32_32x32x16_bf16 v[50:65], v[140:143], v[80:83], v[50:65]
	s_nop 7
	s_mov_b32 s1, 0xf149f2ca
	v_max3_f32 v66, v34, v35, v36
	v_max3_f32 v66, v66, v37, v38
	v_max3_f32 v66, v66, v39, v40
	v_max3_f32 v66, v66, v41, v42
	v_max3_f32 v66, v66, v43, v44
	v_max3_f32 v66, v66, v45, v46
	v_max3_f32 v66, v66, v47, v48
	v_max3_f32 v66, v66, v49, v50
	v_max3_f32 v66, v66, v51, v52
	v_max3_f32 v66, v66, v53, v54
	v_max3_f32 v66, v66, v55, v56
	v_max3_f32 v66, v66, v57, v58
	v_max3_f32 v66, v66, v59, v60
	v_max3_f32 v66, v66, v61, v62
	v_max3_f32 v66, v66, v63, v64
	v_max_f32_e32 v66, v66, v65
	v_cmp_lt_i32_e32 vcc, v242, v241
	v_mul_f32_e32 v66, 0x3e38aa3b, v66
	v_max_f32_e32 v66, s1, v66
	v_cndmask_b32_e32 v84, v240, v242, vcc
	v_lshlrev_b32_e32 v84, 2, v84
	ds_bpermute_b32 v84, v84, v66
	s_waitcnt lgkmcnt(0)
	v_max3_f32 v140, v131, v66, v84
	v_fma_f32 v34, v34, s0, -v140
	v_exp_f32_e32 v142, v34
	v_fma_f32 v34, v50, s0, -v140
	v_exp_f32_e32 v165, v34
	v_fma_f32 v34, v35, s0, -v140
	v_exp_f32_e32 v66, v34
	v_fma_f32 v34, v51, s0, -v140
	v_exp_f32_e32 v84, v34
	v_add_f32_e32 v85, v165, v142
	v_pk_add_f32 v[34:35], v[84:85], v[66:67]
	s_nop 0
	v_pk_add_f32 v[86:87], v[34:35], v[34:35] op_sel_hi:[0,1]
	v_fma_f32 v34, v36, s0, -v140
	v_exp_f32_e32 v85, v34
	v_fma_f32 v34, v52, s0, -v140
	v_exp_f32_e32 v170, v34
	v_fma_f32 v34, v37, s0, -v140
	v_exp_f32_e32 v86, v34
	v_fma_f32 v34, v53, s0, -v140
	v_exp_f32_e32 v90, v34
	v_add_f32_e32 v91, v170, v85
	v_pk_add_f32 v[34:35], v[90:91], v[86:87]
	s_nop 0
	v_pk_add_f32 v[88:89], v[34:35], v[34:35] op_sel_hi:[0,1]
	v_fma_f32 v34, v38, s0, -v140
	v_exp_f32_e32 v87, v34
	v_fma_f32 v34, v54, s0, -v140
	v_exp_f32_e32 v91, v34
	v_fma_f32 v34, v39, s0, -v140
	v_exp_f32_e32 v88, v34
	v_fma_f32 v34, v55, s0, -v140
	v_exp_f32_e32 v150, v34
	v_add_f32_e32 v151, v91, v87
	v_pk_add_f32 v[34:35], v[150:151], v[88:89]
	s_nop 0
	v_pk_add_f32 v[146:147], v[34:35], v[34:35] op_sel_hi:[0,1]
	v_fma_f32 v34, v40, s0, -v140
	v_exp_f32_e32 v89, v34
	v_fma_f32 v34, v56, s0, -v140
	v_exp_f32_e32 v151, v34
	v_fma_f32 v34, v41, s0, -v140
	v_exp_f32_e32 v146, v34
	v_fma_f32 v34, v57, s0, -v140
	v_exp_f32_e32 v152, v34
	v_add_f32_e32 v153, v151, v89
	v_pk_add_f32 v[34:35], v[152:153], v[146:147]
	s_nop 0
	v_pk_add_f32 v[148:149], v[34:35], v[34:35] op_sel_hi:[0,1]
	v_fma_f32 v34, v42, s0, -v140
	v_exp_f32_e32 v147, v34
	v_fma_f32 v34, v58, s0, -v140
	v_exp_f32_e32 v153, v34
	v_fma_f32 v34, v43, s0, -v140
	v_exp_f32_e32 v148, v34
	v_fma_f32 v34, v59, s0, -v140
	v_exp_f32_e32 v154, v34
	v_add_f32_e32 v155, v153, v147
	v_pk_add_f32 v[34:35], v[154:155], v[148:149]
	s_nop 0
	v_pk_add_f32 v[156:157], v[34:35], v[34:35] op_sel_hi:[0,1]
	v_fma_f32 v34, v44, s0, -v140
	v_exp_f32_e32 v149, v34
	v_fma_f32 v34, v60, s0, -v140
	v_exp_f32_e32 v155, v34
	v_fma_f32 v34, v45, s0, -v140
	v_exp_f32_e32 v156, v34
	v_fma_f32 v34, v61, s0, -v140
	v_exp_f32_e32 v158, v34
	v_add_f32_e32 v159, v155, v149
	v_pk_add_f32 v[34:35], v[158:159], v[156:157]
	s_nop 0
	v_pk_add_f32 v[160:161], v[34:35], v[34:35] op_sel_hi:[0,1]
	v_fma_f32 v34, v46, s0, -v140
; #define LAS __attribute__((address_space(3)))
; #define MFMA32(a, b, c) __builtin_amdgcn_mfma_f32_32x32x16_bf16((a), (b), (c), 0, 0, 0)
; __device__ __forceinline__ s16x4 tr_read(LAS unsigned char* p) { return __builtin_bit_cast(s16x4, __builtin_amdgcn_ds_read_tr16_b64_v4i16((LAS v4i16_t*)p)); }
;     __device__ __forceinline__ float operator()(float s, int kc, int h, int qr) const { const int d = dk + kc + 4 * h - qr; return (d >= -128 && d <= 128) ? s * (ATT_SCALE * LOG2E) : NEG_BIG; }
; template <class ScoreFn>
; __device__ __forceinline__ void attn_step(AttnState& st, const bf16x8 (&qf)[4], LAS unsigned char* kb, LAS unsigned char* vb, int lane, const ScoreFn& sf) {
;     ...
;     LAS unsigned char* vrow = vb + (4 * h + q) * KVP + (p & 1) * 8;
;     LAS unsigned char* vp0 = vrow + (((2 * dhalf + (p >> 1)) ^ (4 * h + q)) << 4); LAS unsigned char* vp1 = vrow + (((4 + 2 * dhalf + (p >> 1)) ^ (4 * h + q)) << 4);
; #pragma unroll
;     for (int ks = 0; ks < 4; ++ks) {
;         const s16x4 l0 = tr_read(vp0 + (16 * ks) * KVP), h0 = tr_read(vp0 + (16 * ks + 8) * KVP);
;         const s16x4 l1 = tr_read(vp1 + (16 * ks) * KVP), h1 = tr_read(vp1 + (16 * ks + 8) * KVP);
;         const bf16x8 v0 = (bf16x8){l0[0], l0[1], l0[2], l0[3], h0[0], h0[1], h0[2], h0[3]};
;         const bf16x8 v1 = (bf16x8){l1[0], l1[1], l1[2], l1[3], h1[0], h1[1], h1[2], h1[3]};
;         const bf16x8 pf = __builtin_bit_cast(bf16x8, pw[ks]);
;         st.o0 = MFMA32(v0, pf, st.o0); st.o1 = MFMA32(v1, pf, st.o1);
;     }
;     __device__ __forceinline__ float operator()(float s, int kc, int, int) const {
;         const float b = *(const LAS float*)(tbs + 4 * kc);
;         return (kc >= lo4 && kc < lo4 + 16) ? fmaf(s, ATT_SCALE * LOG2E, b) : NEG_BIG;
;     }
; template <bool ISB>
; __device__ __forceinline__ void attn_wg_item(Frame& F, int l, int idx) {
;     ...
;         else { const int gr = r0 + (w >> 1); int kr0 = gr - 4; kr0 = kr0 < 0 ? 0 : (kr0 > 120 ? 120 : kr0); const int kr = kmin + s;
;             if (kr >= kr0 && kr < kr0 + 8) { const int cq = 32 * (w & 1) + (lane & 31), hh = lane >> 5; int cs = cq - 8; cs = cs < 0 ? 0 : (cs > 48 ? 48 : cs);
;                 ScoreNb sf{(LAS unsigned char*)(tab + 64) + ((kr - gr + 7) * 31 + 15 - cq + 4 * hh) * 4, cs - 4 * hh}; attn_step(st, qf, cur, cur + KV_TILE, lane, sf); } }
	v_exp_f32_e32 v157, v34
	v_fma_f32 v34, v62, s0, -v140
	v_exp_f32_e32 v159, v34
	v_fma_f32 v34, v47, s0, -v140
	v_exp_f32_e32 v160, v34
	v_fma_f32 v34, v63, s0, -v140
	v_exp_f32_e32 v162, v34
	v_add_f32_e32 v163, v159, v157
	v_pk_add_f32 v[34:35], v[162:163], v[160:161]
	s_nop 0
	v_pk_add_f32 v[166:167], v[34:35], v[34:35] op_sel_hi:[0,1]
	v_fma_f32 v34, v48, s0, -v140
	v_exp_f32_e32 v161, v34
	v_fma_f32 v34, v64, s0, -v140
	v_exp_f32_e32 v163, v34
	v_fma_f32 v34, v49, s0, -v140
	v_exp_f32_e32 v166, v34
	v_fma_f32 v34, v65, s0, -v140
	v_exp_f32_e32 v168, v34
	v_sub_f32_e32 v34, v131, v140
	v_exp_f32_e32 v50, v34
	v_add_f32_e32 v169, v163, v161
	v_pk_add_f32 v[34:35], v[168:169], v[166:167]
	v_pk_mul_f32 v[48:49], v[32:33], v[50:51] op_sel_hi:[1,0]
	v_add_f32_e32 v141, v34, v35
	v_fmac_f32_e32 v141, v130, v50
	v_pk_mul_f32 v[46:47], v[30:31], v[50:51] op_sel_hi:[1,0]
	v_pk_mul_f32 v[44:45], v[28:29], v[50:51] op_sel_hi:[1,0]
	v_pk_mul_f32 v[42:43], v[26:27], v[50:51] op_sel_hi:[1,0]
	v_pk_mul_f32 v[40:41], v[24:25], v[50:51] op_sel_hi:[1,0]
	v_pk_mul_f32 v[38:39], v[22:23], v[50:51] op_sel_hi:[1,0]
	v_pk_mul_f32 v[36:37], v[20:21], v[50:51] op_sel_hi:[1,0]
	v_pk_mul_f32 v[34:35], v[18:19], v[50:51] op_sel_hi:[1,0]
	v_pk_mul_f32 v[64:65], v[16:17], v[50:51] op_sel_hi:[1,0]
	v_pk_mul_f32 v[62:63], v[14:15], v[50:51] op_sel_hi:[1,0]
	v_pk_mul_f32 v[60:61], v[12:13], v[50:51] op_sel_hi:[1,0]
	v_pk_mul_f32 v[58:59], v[10:11], v[50:51] op_sel_hi:[1,0]
	v_pk_mul_f32 v[56:57], v[8:9], v[50:51] op_sel_hi:[1,0]
	v_pk_mul_f32 v[54:55], v[6:7], v[50:51] op_sel_hi:[1,0]
	v_pk_mul_f32 v[52:53], v[4:5], v[50:51] op_sel_hi:[1,0]
	v_pk_mul_f32 v[50:51], v[2:3], v[50:51] op_sel_hi:[1,0]
	v_cvt_pk_bf16_f32 v142, v142, v66
	v_cvt_pk_bf16_f32 v144, v87, v88
	v_cvt_pk_bf16_f32 v145, v89, v146
	v_cvt_pk_bf16_f32 v88, v165, v84
	v_cvt_pk_bf16_f32 v89, v170, v90
	v_cvt_pk_bf16_f32 v90, v91, v150
	v_cvt_pk_bf16_f32 v91, v151, v152
	v_cvt_pk_bf16_f32 v84, v153, v154
	ds_read_b64_tr_b16 v[150:151], v134
	v_cvt_pk_bf16_f32 v143, v85, v86
	v_cvt_pk_bf16_f32 v85, v155, v158
	ds_read_b64_tr_b16 v[152:153], v133
	ds_read_b64_tr_b16 v[154:155], v135
	v_cvt_pk_bf16_f32 v146, v147, v148
	v_cvt_pk_bf16_f32 v147, v149, v156
	v_cvt_pk_bf16_f32 v148, v157, v160
	ds_read_b64_tr_b16 v[156:157], v132
	s_waitcnt lgkmcnt(2)
	v_mfma_f32_32x32x16_bf16 v[34:49], v[150:153], v[142:145], v[34:49]
	v_cvt_pk_bf16_f32 v149, v161, v166
	v_cvt_pk_bf16_f32 v86, v159, v162
	v_cvt_pk_bf16_f32 v87, v163, v168
	s_mov_b64 s[74:75], 0
	s_waitcnt lgkmcnt(0)
	v_mfma_f32_32x32x16_bf16 v[50:65], v[154:157], v[142:145], v[50:65]
	ds_read_b64_tr_b16 v[142:143], v129
	ds_read_b64_tr_b16 v[144:145], v128
	ds_read_b64_tr_b16 v[150:151], v127
	ds_read_b64_tr_b16 v[152:153], v126
	s_waitcnt lgkmcnt(2)
	v_mfma_f32_32x32x16_bf16 v[34:49], v[142:145], v[146:149], v[34:49]
	ds_read_b64_tr_b16 v[142:143], v125
	ds_read_b64_tr_b16 v[144:145], v124
	s_waitcnt lgkmcnt(2)
	v_mfma_f32_32x32x16_bf16 v[50:65], v[150:153], v[146:149], v[50:65]
	ds_read_b64_tr_b16 v[146:147], v123
	ds_read_b64_tr_b16 v[148:149], v122
	s_waitcnt lgkmcnt(2)
	v_mfma_f32_32x32x16_bf16 v[34:49], v[142:145], v[88:91], v[34:49]
	s_waitcnt lgkmcnt(0)
	v_mfma_f32_32x32x16_bf16 v[50:65], v[146:149], v[88:91], v[50:65]
	ds_read_b64_tr_b16 v[88:89], v121
	ds_read_b64_tr_b16 v[90:91], v120
	ds_read_b64_tr_b16 v[142:143], v119
	ds_read_b64_tr_b16 v[144:145], v118
	s_waitcnt lgkmcnt(2)
	v_mfma_f32_32x32x16_bf16 v[34:49], v[88:91], v[84:87], v[34:49]
	s_waitcnt lgkmcnt(0)
	v_mfma_f32_32x32x16_bf16 v[50:65], v[142:145], v[84:87], v[50:65]
.LBB0_620:
	s_andn2_b64 vcc, exec, s[74:75]
	s_cbranch_vccnz .LBB0_624
	s_add_i32 s1, s76, s82
	v_cmp_ge_u32_e32 vcc, s1, v94
	v_cmp_lt_u32_e64 s[74:75], s1, v95
	s_and_b64 s[2:3], vcc, s[74:75]
	s_andn2_b64 vcc, exec, s[2:3]
	s_cbranch_vccnz .LBB0_623
	s_mov_b32 s1, 0
	s_nop 0
	v_add_u32_e32 v38, s1, v139
	ds_read_b128 v[34:37], v38
	ds_read_b128 v[50:53], v38 offset:4096
	v_add_u32_e32 v58, s1, v138
	ds_read_b128 v[54:57], v58
	ds_read_b128 v[84:87], v58 offset:4096
	v_add_u32_e32 v59, s1, v137
	v_add_u32_e32 v58, s1, v136
	v_add_u32_e32 v66, 0, v109
	s_waitcnt lgkmcnt(0)
	v_mfma_f32_32x32x16_bf16 v[34:49], v[34:37], v[68:71], 0
	ds_read_b128 v[88:91], v59 offset:4096
	ds_read_b128 v[136:139], v58 offset:4096
	v_mfma_f32_32x32x16_bf16 v[34:49], v[54:57], v[72:75], v[34:49]
	ds_read_b128 v[54:57], v59
	v_add_u32_e32 v59, 0x184a0, v66
	s_waitcnt lgkmcnt(0)
	v_mfma_f32_32x32x16_bf16 v[34:49], v[54:57], v[76:79], v[34:49]
	ds_read_b128 v[54:57], v58
	s_waitcnt lgkmcnt(0)
	v_mfma_f32_32x32x16_bf16 v[34:49], v[54:57], v[80:83], v[34:49]
	v_add_u32_e32 v54, 0x184a8, v66
	v_add_u32_e32 v55, 0x184c0, v66
	v_add_u32_e32 v56, 0x184c8, v66
	ds_read2_b32 v[140:141], v59 offset1:1
	ds_read2_b32 v[142:143], v54 offset1:1
	ds_read2_b32 v[144:145], v55 offset1:1
	ds_read2_b32 v[146:147], v56 offset1:1
	v_add_u32_e32 v54, 0x184e0, v66
	v_add_u32_e32 v55, 0x184e8, v66
	v_add_u32_e32 v56, 0x18500, v66
	v_add_u32_e32 v57, 0x18508, v66
	ds_read2_b32 v[148:149], v54 offset1:1
	ds_read2_b32 v[150:151], v55 offset1:1
	ds_read2_b32 v[152:153], v56 offset1:1
	ds_read2_b32 v[154:155], v57 offset1:1
	v_mfma_f32_32x32x16_bf16 v[50:65], v[50:53], v[68:71], 0
	v_mfma_f32_32x32x16_bf16 v[50:65], v[84:87], v[72:75], v[50:65]
	v_add_u32_e32 v84, 0x18520, v66
	v_add_u32_e32 v86, 0x18528, v66
	v_mfma_f32_32x32x16_bf16 v[50:65], v[88:91], v[76:79], v[50:65]
	v_add_u32_e32 v88, 0x18540, v66
	v_add_u32_e32 v90, 0x18548, v66
	ds_read2_b32 v[84:85], v84 offset1:1
	ds_read2_b32 v[86:87], v86 offset1:1
	ds_read2_b32 v[88:89], v88 offset1:1
	ds_read2_b32 v[90:91], v90 offset1:1
	v_mfma_f32_32x32x16_bf16 v[50:65], v[136:139], v[80:83], v[50:65]
	v_add_u32_e32 v136, 0x18560, v66
	v_add_u32_e32 v138, 0x18568, v66
	v_add_u32_e32 v156, 0x18580, v66
	v_add_u32_e32 v66, 0x18588, v66
	ds_read2_b32 v[136:137], v136 offset1:1
	ds_read2_b32 v[138:139], v138 offset1:1
	ds_read2_b32 v[156:157], v156 offset1:1
	ds_read2_b32 v[158:159], v66 offset1:1
	s_waitcnt lgkmcnt(0)
; #define LAS __attribute__((address_space(3)))
;     __device__ __forceinline__ float operator()(float s, int kc, int h, int qr) const { const int d = dk + kc + 4 * h - qr; return (d >= -128 && d <= 128) ? s * (ATT_SCALE * LOG2E) : NEG_BIG; }
; template <class ScoreFn>
; __device__ __forceinline__ void attn_step(AttnState& st, const bf16x8 (&qf)[4], LAS unsigned char* kb, LAS unsigned char* vb, int lane, const ScoreFn& sf) {
;     ...
; #pragma unroll
;     for (int i = 0; i < 16; ++i) { s0[i] = sf(s0[i], (i & 3) + 8 * (i >> 2), h, r); mt = fmaxf(mt, s0[i]); if ((i & 7) == 7) __builtin_amdgcn_sched_barrier(0); }
; #pragma unroll
;     for (int i = 0; i < 16; ++i) { s1[i] = sf(s1[i], 32 + (i & 3) + 8 * (i >> 2), h, r); mt = fmaxf(mt, s1[i]); if ((i & 7) == 7) __builtin_amdgcn_sched_barrier(0); }
;     mt = fmaxf(mt, __shfl_xor(mt, 32));
;     __device__ __forceinline__ float operator()(float s, int kc, int, int) const {
;         const float b = *(const LAS float*)(tbs + 4 * kc);
;         return (kc >= lo4 && kc < lo4 + 16) ? fmaf(s, ATT_SCALE * LOG2E, b) : NEG_BIG;
;     }
	v_fmamk_f32 v34, v34, 0x3e38aa3b, v140
	v_fmac_f32_e32 v141, 0x3e38aa3b, v35
	v_cndmask_b32_e64 v34, v250, v34, s[6:7]
	v_cndmask_b32_e64 v35, v250, v141, s[8:9]
	s_mov_b32 s1, 0xf149f2ca
	v_fmamk_f32 v36, v36, 0x3e38aa3b, v142
	v_fmac_f32_e32 v143, 0x3e38aa3b, v37
	v_max3_f32 v66, v34, s1, v35
	v_cndmask_b32_e64 v140, v250, v36, s[10:11]
	v_cndmask_b32_e64 v141, v250, v143, s[12:13]
	v_fmamk_f32 v37, v38, 0x3e38aa3b, v144
	v_fmac_f32_e32 v145, 0x3e38aa3b, v39
	v_max3_f32 v36, v66, v140, v141
	v_cndmask_b32_e64 v142, v250, v37, s[14:15]
	v_cndmask_b32_e64 v143, v250, v145, s[16:17]
	v_fmamk_f32 v37, v40, 0x3e38aa3b, v146
	v_fmac_f32_e32 v147, 0x3e38aa3b, v41
	v_max3_f32 v36, v36, v142, v143
	v_cndmask_b32_e64 v144, v250, v37, s[18:19]
	v_cndmask_b32_e64 v145, v250, v147, s[20:21]
	v_fmamk_f32 v37, v42, 0x3e38aa3b, v148
	v_fmac_f32_e32 v149, 0x3e38aa3b, v43
	v_max3_f32 v36, v36, v144, v145
	v_cndmask_b32_e64 v146, v250, v37, s[22:23]
	v_cndmask_b32_e64 v43, v250, v149, s[24:25]
	v_fmamk_f32 v37, v44, 0x3e38aa3b, v150
	v_fmac_f32_e32 v151, 0x3e38aa3b, v45
	v_max3_f32 v36, v36, v146, v43
	v_cndmask_b32_e64 v147, v250, v37, s[26:27]
	v_cndmask_b32_e64 v148, v250, v151, s[28:29]
	v_fmamk_f32 v37, v46, 0x3e38aa3b, v152
	v_fmac_f32_e32 v153, 0x3e38aa3b, v47
	v_max3_f32 v36, v36, v147, v148
	v_cndmask_b32_e64 v46, v250, v37, s[30:31]
	v_cndmask_b32_e64 v47, v250, v153, s[34:35]
	v_fmamk_f32 v37, v48, 0x3e38aa3b, v154
	v_fmac_f32_e32 v155, 0x3e38aa3b, v49
	v_max3_f32 v36, v36, v46, v47
	v_cndmask_b32_e64 v149, v250, v37, s[36:37]
	v_cndmask_b32_e64 v150, v250, v155, s[38:39]
	v_fmamk_f32 v37, v50, 0x3e38aa3b, v84
	v_fmac_f32_e32 v85, 0x3e38aa3b, v51
	v_max3_f32 v36, v36, v149, v150
	v_cndmask_b32_e64 v37, v250, v37, s[40:41]
	v_cndmask_b32_e64 v38, v250, v85, s[42:43]
	v_fmamk_f32 v39, v52, 0x3e38aa3b, v86
	v_fmac_f32_e32 v87, 0x3e38aa3b, v53
	v_max3_f32 v36, v36, v37, v38
	v_cndmask_b32_e64 v39, v250, v39, s[44:45]
	v_cndmask_b32_e64 v40, v250, v87, s[46:47]
	v_fmamk_f32 v41, v54, 0x3e38aa3b, v88
	v_fmac_f32_e32 v89, 0x3e38aa3b, v55
	v_max3_f32 v36, v36, v39, v40
	v_cndmask_b32_e64 v44, v250, v41, s[48:49]
	v_cndmask_b32_e64 v45, v250, v89, s[50:51]
	v_fmamk_f32 v41, v56, 0x3e38aa3b, v90
	v_fmac_f32_e32 v91, 0x3e38aa3b, v57
	v_max3_f32 v36, v36, v44, v45
	v_cndmask_b32_e64 v50, v250, v41, s[52:53]
	v_cndmask_b32_e64 v51, v250, v91, s[54:55]
	v_fmamk_f32 v41, v58, 0x3e38aa3b, v136
	v_fmac_f32_e32 v137, 0x3e38aa3b, v59
	v_max3_f32 v36, v36, v50, v51
	v_cndmask_b32_e64 v56, v250, v41, s[56:57]
	v_cndmask_b32_e64 v57, v250, v137, s[58:59]
	v_fmamk_f32 v41, v60, 0x3e38aa3b, v138
	v_fmac_f32_e32 v139, 0x3e38aa3b, v61
	v_max3_f32 v36, v36, v56, v57
	v_cndmask_b32_e64 v60, v250, v41, s[60:61]
	v_cndmask_b32_e64 v61, v250, v139, s[62:63]
	v_fmamk_f32 v41, v62, 0x3e38aa3b, v156
	v_fmac_f32_e32 v157, 0x3e38aa3b, v63
	v_max3_f32 v36, v36, v60, v61
	v_cndmask_b32_e64 v84, v250, v41, s[64:65]
	v_cndmask_b32_e64 v85, v250, v157, s[66:67]
	v_fmamk_f32 v41, v64, 0x3e38aa3b, v158
	v_fmac_f32_e32 v159, 0x3e38aa3b, v65
	v_cmp_lt_i32_e32 vcc, v242, v241
	v_max3_f32 v36, v36, v84, v85
	v_cndmask_b32_e64 v86, v250, v41, s[68:69]
	v_cndmask_b32_e64 v87, v250, v159, s[70:71]
	v_cndmask_b32_e32 v41, v240, v242, vcc
	v_max3_f32 v36, v36, v86, v87
	v_lshlrev_b32_e32 v41, 2, v41
	ds_bpermute_b32 v41, v41, v36
	s_waitcnt lgkmcnt(0)
; #define LAS __attribute__((address_space(3)))
; #define MFMA32(a, b, c) __builtin_amdgcn_mfma_f32_32x32x16_bf16((a), (b), (c), 0, 0, 0)
; __device__ __forceinline__ unsigned cvtpk(float lo, float hi) { return pg8::cvt_pk_bf16(lo, hi); }
; template <class ScoreFn>
; __device__ __forceinline__ void attn_step(AttnState& st, const bf16x8 (&qf)[4], LAS unsigned char* kb, LAS unsigned char* vb, int lane, const ScoreFn& sf) {
;     ...
;     mt = fmaxf(mt, __shfl_xor(mt, 32));
;     const float mn = fmaxf(st.m, mt), alpha = __builtin_amdgcn_exp2f(st.m - mn);
;     float ps = 0.f;
; #pragma unroll
;     for (int i = 0; i < 16; ++i) { s0[i] = __builtin_amdgcn_exp2f(s0[i] - mn); s1[i] = __builtin_amdgcn_exp2f(s1[i] - mn); ps += s0[i] + s1[i]; }
;     st.l = st.l * alpha + ps; st.m = mn;
; #pragma unroll
;     for (int i = 0; i < 16; ++i) { st.o0[i] *= alpha; st.o1[i] *= alpha; }
;     __builtin_amdgcn_sched_barrier(0);
;     v4u pw[4];
;     pw[0].x = cvtpk(s0[0], s0[1]); pw[0].y = cvtpk(s0[2], s0[3]); pw[0].z = cvtpk(s0[4], s0[5]); pw[0].w = cvtpk(s0[6], s0[7]);
;     pw[1].x = cvtpk(s0[8], s0[9]); pw[1].y = cvtpk(s0[10], s0[11]); pw[1].z = cvtpk(s0[12], s0[13]); pw[1].w = cvtpk(s0[14], s0[15]);
;     pw[2].x = cvtpk(s1[0], s1[1]); pw[2].y = cvtpk(s1[2], s1[3]); pw[2].z = cvtpk(s1[4], s1[5]); pw[2].w = cvtpk(s1[6], s1[7]);
;     pw[3].x = cvtpk(s1[8], s1[9]); pw[3].y = cvtpk(s1[10], s1[11]); pw[3].z = cvtpk(s1[12], s1[13]); pw[3].w = cvtpk(s1[14], s1[15]);
;     const int i16 = lane & 15, q = i16 >> 2, p = i16 & 3, dhalf = (lane >> 4) & 1;
;     LAS unsigned char* vrow = vb + (4 * h + q) * KVP + (p & 1) * 8;
;     LAS unsigned char* vp0 = vrow + (((2 * dhalf + (p >> 1)) ^ (4 * h + q)) << 4); LAS unsigned char* vp1 = vrow + (((4 + 2 * dhalf + (p >> 1)) ^ (4 * h + q)) << 4);
; #pragma unroll
;     for (int ks = 0; ks < 4; ++ks) {
;         const s16x4 l0 = tr_read(vp0 + (16 * ks) * KVP), h0 = tr_read(vp0 + (16 * ks + 8) * KVP);
;         const s16x4 l1 = tr_read(vp1 + (16 * ks) * KVP), h1 = tr_read(vp1 + (16 * ks + 8) * KVP);
;         const bf16x8 v0 = (bf16x8){l0[0], l0[1], l0[2], l0[3], h0[0], h0[1], h0[2], h0[3]};
;         const bf16x8 v1 = (bf16x8){l1[0], l1[1], l1[2], l1[3], h1[0], h1[1], h1[2], h1[3]};
;         const bf16x8 pf = __builtin_bit_cast(bf16x8, pw[ks]);
;         st.o0 = MFMA32(v0, pf, st.o0); st.o1 = MFMA32(v1, pf, st.o1);
;     }
	v_max3_f32 v42, v131, v36, v41
	v_sub_f32_e32 v34, v34, v42
	v_exp_f32_e32 v88, v34
	v_sub_f32_e32 v34, v37, v42
	v_exp_f32_e32 v89, v34
	v_sub_f32_e32 v34, v35, v42
	v_exp_f32_e32 v66, v34
	v_sub_f32_e32 v34, v38, v42
	v_exp_f32_e32 v34, v34
	v_add_f32_e32 v35, v89, v88
	v_sub_f32_e32 v38, v40, v42
	v_exp_f32_e32 v40, v38
	v_pk_add_f32 v[36:37], v[34:35], v[66:67]
	v_sub_f32_e32 v35, v140, v42
	v_pk_add_f32 v[36:37], v[36:37], v[36:37] op_sel_hi:[0,1]
	v_sub_f32_e32 v36, v39, v42
	v_exp_f32_e32 v35, v35
	v_exp_f32_e32 v90, v36
	v_sub_f32_e32 v36, v141, v42
	v_exp_f32_e32 v36, v36
	v_sub_f32_e32 v43, v43, v42
	v_add_f32_e32 v41, v90, v35
	v_pk_add_f32 v[38:39], v[40:41], v[36:37]
	s_nop 0
	v_pk_add_f32 v[38:39], v[38:39], v[38:39] op_sel_hi:[0,1]
	v_sub_f32_e32 v37, v142, v42
	v_sub_f32_e32 v38, v44, v42
	v_exp_f32_e32 v37, v37
	v_exp_f32_e32 v41, v38
	v_sub_f32_e32 v38, v143, v42
	v_sub_f32_e32 v44, v45, v42
	v_exp_f32_e32 v38, v38
	v_exp_f32_e32 v52, v44
	v_add_f32_e32 v53, v41, v37
	v_pk_add_f32 v[44:45], v[52:53], v[38:39]
	s_nop 0
	v_pk_add_f32 v[48:49], v[44:45], v[44:45] op_sel_hi:[0,1]
	v_sub_f32_e32 v44, v50, v42
	v_sub_f32_e32 v39, v144, v42
	v_exp_f32_e32 v53, v44
	v_sub_f32_e32 v44, v145, v42
	v_exp_f32_e32 v39, v39
	v_exp_f32_e32 v48, v44
	v_sub_f32_e32 v44, v51, v42
	v_exp_f32_e32 v54, v44
	v_add_f32_e32 v55, v53, v39
	v_pk_add_f32 v[44:45], v[54:55], v[48:49]
	s_nop 0
	v_pk_add_f32 v[50:51], v[44:45], v[44:45] op_sel_hi:[0,1]
	v_sub_f32_e32 v44, v146, v42
	v_exp_f32_e32 v49, v44
	v_sub_f32_e32 v44, v56, v42
	v_exp_f32_e32 v55, v44
	v_exp_f32_e32 v50, v43
	v_sub_f32_e32 v43, v57, v42
	v_exp_f32_e32 v56, v43
	v_add_f32_e32 v57, v55, v49
	v_sub_f32_e32 v43, v147, v42
	v_exp_f32_e32 v43, v43
	v_pk_add_f32 v[44:45], v[56:57], v[50:51]
	s_nop 0
	v_pk_add_f32 v[58:59], v[44:45], v[44:45] op_sel_hi:[0,1]
	v_sub_f32_e32 v44, v60, v42
	v_exp_f32_e32 v57, v44
	v_sub_f32_e32 v44, v148, v42
	v_exp_f32_e32 v58, v44
	v_sub_f32_e32 v44, v61, v42
	v_exp_f32_e32 v60, v44
	v_add_f32_e32 v61, v57, v43
	v_pk_add_f32 v[44:45], v[60:61], v[58:59]
	s_nop 0
	v_pk_add_f32 v[62:63], v[44:45], v[44:45] op_sel_hi:[0,1]
	v_sub_f32_e32 v44, v46, v42
	v_exp_f32_e32 v51, v44
	v_sub_f32_e32 v44, v84, v42
	v_exp_f32_e32 v59, v44
	v_sub_f32_e32 v44, v47, v42
	v_exp_f32_e32 v62, v44
	v_sub_f32_e32 v44, v85, v42
	v_exp_f32_e32 v64, v44
	v_add_f32_e32 v65, v59, v51
	v_pk_add_f32 v[44:45], v[64:65], v[62:63]
	s_nop 0
	v_pk_add_f32 v[84:85], v[44:45], v[44:45] op_sel_hi:[0,1]
	v_sub_f32_e32 v44, v149, v42
	v_exp_f32_e32 v61, v44
	v_sub_f32_e32 v44, v86, v42
	v_exp_f32_e32 v63, v44
	v_sub_f32_e32 v44, v150, v42
	v_exp_f32_e32 v84, v44
	v_sub_f32_e32 v44, v87, v42
	v_exp_f32_e32 v86, v44
	v_sub_f32_e32 v44, v131, v42
	v_exp_f32_e32 v44, v44
	v_add_f32_e32 v87, v63, v61
	v_pk_add_f32 v[46:47], v[86:87], v[84:85]
	v_pk_mul_f32 v[32:33], v[32:33], v[44:45] op_sel_hi:[1,0]
	v_add_f32_e32 v65, v46, v47
	v_pk_mul_f32 v[30:31], v[30:31], v[44:45] op_sel_hi:[1,0]
	v_pk_mul_f32 v[28:29], v[28:29], v[44:45] op_sel_hi:[1,0]
	v_pk_mul_f32 v[26:27], v[26:27], v[44:45] op_sel_hi:[1,0]
	v_pk_mul_f32 v[24:25], v[24:25], v[44:45] op_sel_hi:[1,0]
	v_pk_mul_f32 v[22:23], v[22:23], v[44:45] op_sel_hi:[1,0]
	v_pk_mul_f32 v[20:21], v[20:21], v[44:45] op_sel_hi:[1,0]
	v_pk_mul_f32 v[18:19], v[18:19], v[44:45] op_sel_hi:[1,0]
	v_pk_mul_f32 v[16:17], v[16:17], v[44:45] op_sel_hi:[1,0]
	v_pk_mul_f32 v[14:15], v[14:15], v[44:45] op_sel_hi:[1,0]
	v_pk_mul_f32 v[12:13], v[12:13], v[44:45] op_sel_hi:[1,0]
	v_pk_mul_f32 v[10:11], v[10:11], v[44:45] op_sel_hi:[1,0]
	v_pk_mul_f32 v[8:9], v[8:9], v[44:45] op_sel_hi:[1,0]
	v_pk_mul_f32 v[6:7], v[6:7], v[44:45] op_sel_hi:[1,0]
	v_pk_mul_f32 v[4:5], v[4:5], v[44:45] op_sel_hi:[1,0]
	v_pk_mul_f32 v[2:3], v[2:3], v[44:45] op_sel_hi:[1,0]
	v_fmac_f32_e32 v65, v130, v44
	v_cvt_pk_bf16_f32 v47, v39, v48
	v_cvt_pk_bf16_f32 v48, v49, v50
	v_cvt_pk_bf16_f32 v49, v43, v58
	v_cvt_pk_bf16_f32 v46, v37, v38
	v_cvt_pk_bf16_f32 v38, v89, v34
	v_cvt_pk_bf16_f32 v39, v90, v40
	v_cvt_pk_bf16_f32 v40, v41, v52
	v_cvt_pk_bf16_f32 v41, v53, v54
	v_cvt_pk_bf16_f32 v34, v55, v56
	ds_read_b64_tr_b16 v[52:53], v134
	v_cvt_pk_bf16_f32 v45, v35, v36
	v_cvt_pk_bf16_f32 v35, v57, v60
	ds_read_b64_tr_b16 v[54:55], v133
	ds_read_b64_tr_b16 v[56:57], v135
	v_cvt_pk_bf16_f32 v36, v59, v64
	ds_read_b64_tr_b16 v[58:59], v132
	v_cvt_pk_bf16_f32 v44, v88, v66
	v_cvt_pk_bf16_f32 v50, v51, v62
	s_waitcnt lgkmcnt(2)
	v_mfma_f32_32x32x16_bf16 v[18:33], v[52:55], v[44:47], v[18:33]
	v_cvt_pk_bf16_f32 v51, v61, v84
	v_cvt_pk_bf16_f32 v37, v63, v86
	v_mov_b32_e32 v130, v65
	v_mov_b32_e32 v131, v42
	s_waitcnt lgkmcnt(0)
	v_mfma_f32_32x32x16_bf16 v[2:17], v[56:59], v[44:47], v[2:17]
	ds_read_b64_tr_b16 v[44:45], v129
	ds_read_b64_tr_b16 v[46:47], v128
	ds_read_b64_tr_b16 v[52:53], v127
	ds_read_b64_tr_b16 v[54:55], v126
	s_waitcnt lgkmcnt(2)
	v_mfma_f32_32x32x16_bf16 v[18:33], v[44:47], v[48:51], v[18:33]
	ds_read_b64_tr_b16 v[44:45], v125
	ds_read_b64_tr_b16 v[46:47], v124
	s_waitcnt lgkmcnt(2)
	v_mfma_f32_32x32x16_bf16 v[2:17], v[52:55], v[48:51], v[2:17]
	ds_read_b64_tr_b16 v[48:49], v123
	ds_read_b64_tr_b16 v[50:51], v122
	s_waitcnt lgkmcnt(2)
	v_mfma_f32_32x32x16_bf16 v[18:33], v[44:47], v[38:41], v[18:33]
	ds_read_b64_tr_b16 v[44:45], v119
	ds_read_b64_tr_b16 v[46:47], v118
	s_waitcnt lgkmcnt(2)
	v_mfma_f32_32x32x16_bf16 v[2:17], v[48:51], v[38:41], v[2:17]
	ds_read_b64_tr_b16 v[38:39], v121
	ds_read_b64_tr_b16 v[40:41], v120
	s_waitcnt lgkmcnt(0)
	v_mfma_f32_32x32x16_bf16 v[18:33], v[38:41], v[34:37], v[18:33]
	v_mfma_f32_32x32x16_bf16 v[2:17], v[44:47], v[34:37], v[2:17]
